# v18 + attention sub-unit table built by 5 waves in parallel instead of one lane
# speedup vs baseline: 1.0147x; 1.0021x over previous
; DI void p_prologue(Frame& F, const Args& a) {
;     ...
;     if (F.bid == 0 && F.tid == 0) { int* tab = (int*)(ws + WS_ATAB); int n = 0;
;         for (int pass = 16; pass >= 4; pass -= 4)
;     ...
;                 for (int h = 0; h < 4; ++h) {
;                     if (pass == 16) { for (int s2 = 0; s2 < nfull; ++s2) tab[n++] = h | (qb << 2) | (s2 << 7) | (16 << 12); }
;                     else if (rem == pass) tab[n++] = h | (qb << 2) | (nfull << 7) | (rem << 12); } }
;         for (; n < 2048; ++n) tab[n] = 0; }
.LBB0_14:
	s_andn2_b64 vcc, exec, s[0:1]
	v_writelane_b32 v254, s88, 0
	s_nop 1
	v_writelane_b32 v254, s89, 1
	s_cbranch_vccnz .LBB0_456
	v_readlane_b32 s4, v253, 41
	v_writelane_b32 v254, s28, 2
	v_readlane_b32 s6, v253, 43
	v_readlane_b32 s7, v253, 44
	v_writelane_b32 v254, s29, 3
	v_mov_b32_e32 v86, v0
	s_mov_b64 s[34:35], s[6:7]
	s_mov_b32 s29, 0
	v_readlane_b32 s3, v253, 0
	s_mov_b32 s30, 0
	s_nop 0
	v_and_b32_e32 v1, 63, v86
	v_or_b32_e32 v1, s3, v1
	v_readfirstlane_b32 s2, v86
	v_cmp_eq_u32_e32 vcc, 0, v1
	v_readlane_b32 s5, v253, 42
	s_and_saveexec_b64 s[8:9], vcc
	s_cbranch_execz .LBB0_65
	s_add_u32 s12, s34, 0x55000000
	s_addc_u32 s13, s35, 0
	s_lshr_b32 s14, s2, 6
	s_cmp_gt_u32 s14, 4
	s_cbranch_scc1 .LBB0_65
	s_cmp_eq_u32 s14, 4
	s_cbranch_scc1 .Ltab_zero
	s_lshl_b32 s30, s14, 5
	s_add_i32 s30, s30, 448
	s_cmp_eq_u32 s14, 0
	s_cselect_b32 s30, 0, s30
	s_lshl_b32 s14, s14, 2
	s_sub_i32 s14, 16, s14

; DI void p_prologue(Frame& F, const Args& a) {
;     ...
;     if (F.bid == 0 && F.tid == 0) { int* tab = (int*)(ws + WS_ATAB); int n = 0;
;         for (int pass = 16; pass >= 4; pass -= 4)
;     ...
;                 for (int h = 0; h < 4; ++h) {
;                     if (pass == 16) { for (int s2 = 0; s2 < nfull; ++s2) tab[n++] = h | (qb << 2) | (s2 << 7) | (16 << 12); }
;                     else if (rem == pass) tab[n++] = h | (qb << 2) | (nfull << 7) | (rem << 12); } }
;         for (; n < 2048; ++n) tab[n] = 0; }
.LBB0_54:
	s_or_b32 s17, s7, s6
	v_mov_b64_e32 v[2:3], s[4:5]
	s_add_u32 s4, s4, 4
	s_addc_u32 s5, s5, 0
	s_addk_i32 s7, 0x80
	v_mov_b32_e32 v1, s17
	s_cmp_eq_u32 s18, s7
	flat_store_dword v[2:3], v1
	s_cbranch_scc0 .LBB0_54
	s_branch .LBB0_18
.LBB0_55:
	s_branch .LBB0_65
.Ltab_zero:
	s_movk_i32 s30, 0x240
